# P0: odd workgroups build SSM operators before the weight copies, even ones after (memory-bound and LDS-bound halves overlap across the chip)
# baseline (speedup 1.0000x reference)
; #define LAS __attribute__((address_space(3)))
; __device__ __forceinline__ void prep_tr(Frame& F) {
;     {   LAS float* scr = (LAS float*)(F.lds + F.wave * 16640);
;         const int gw = F.bid * 8 + F.wave, NGW = F.G * 8;
;         constexpr int I1 = (1024 / 64) * (8192 / 64), I2 = (2048 / 64) * (1024 / 64);
;         for (int it = gw; it < I1 + I2; it += NGW) {
;             int rI = it;
;             if (rI < I1) { transpose_item(F.in[I_CWIN], 1024, 8192, (bf16*)(F.ws + WS_W1), scr, rI, F.lane, RowW1()); continue; } rI -= I1;
; __device__ __forceinline__ void phase_prep(Frame& F) {
;     ...
;     { prep_tr(F); __syncthreads(); prep_ssm(F); }
.LBB0_29:
	s_or_b64 exec, exec, s[0:1]
	s_and_b32 s98, s92, 1
	s_cmp_eq_u32 s98, 0
	s_cbranch_scc1 .Lp0_tr
	v_writelane_b32 v254, s68, 0
	v_writelane_b32 v254, s69, 1
	v_writelane_b32 v254, s72, 2
	v_writelane_b32 v254, s73, 3
	v_and_b32_e32 v1, 60, v2
	s_branch .LBB0_39
.Lp0_tr:
	s_lshl_b32 s0, s92, 3
	v_readlane_b32 s1, v253, 23
	s_add_i32 s2, s1, s0
	s_cmpk_lt_i32 s2, 0xa00
	v_and_b32_e32 v12, 60, v2
	s_cbranch_scc1 .LBB0_31
	v_and_b32_e32 v1, 60, v2
	s_cbranch_execz .LBB0_32
	s_branch .LBB0_39

; #define LAS __attribute__((address_space(3)))
; __device__ __forceinline__ void prep_ssm(Frame& F) {
;     LAS float* fl = (LAS float*)F.lds;
;     const int tid = F.tid;
;     for (int prep_ = 0; prep_ < (PROBE_PREP_PART == 0 ? 2 : 1); ++prep_)
;     for (int item = F.bid; item < 2 * NG; item += F.G) {
;         const int g = item >> 1, r = item & 1;
;         LAS float* Av = fl; LAS float* Fv = fl + 256; LAS float* BBs = fl + 512; LAS float* Cs = fl + 4608; LAS float* PW = fl + 8768;
;         __syncthreads();
;         float pbre[4], pbim[4], pcre[4], pcim[4];
; #pragma unroll
;         for (int it = 0; it < 4; ++it) { const int e = tid + 512 * it, rr = e >> 10, n = (e >> 4) & 63, q = e & 15, p = (e >> 6) & 15, nn = e & 63;
;             pbre[it] = F.in[I_BRE][((size_t)(rr * NG + g) * 64 + n) * 16 + q]; pbim[it] = F.in[I_BIM][((size_t)(rr * NG + g) * 64 + n) * 16 + q];
;             pcre[it] = F.in[I_CRE][((size_t)(rr * NG + g) * 16 + p) * 64 + nn]; pcim[it] = F.in[I_CIM][((size_t)(rr * NG + g) * 16 + p) * 64 + nn]; }
.LBB0_39:
	s_cmp_eq_u32 s98, 2
	s_cbranch_scc1 .LBB0_72
	s_cmpk_gt_i32 s92, 0xff
	s_barrier
	s_cbranch_scc1 .LBB0_71
	v_lshlrev_b32_e32 v2, 1, v0
	v_and_b32_e32 v15, 0x380, v2
	v_lshl_add_u32 v17, v0, 3, 0
	v_lshlrev_b32_e32 v2, 9, v0
	v_lshrrev_b32_e32 v33, 6, v0
	v_add_u32_e32 v19, v17, v2
	v_or_b32_e32 v22, 0x200, v0
	v_sub_u32_e32 v34, 0, v2
	v_mul_u32_u24_e32 v2, 0x41, v33
	v_add_lshl_u32 v58, v2, v209, 3
	v_lshrrev_b32_e32 v2, 1, v22
	v_and_b32_e32 v36, 0x1f8, v2
	v_lshrrev_b32_e32 v2, 6, v22
	v_or_b32_e32 v25, 0x600, v0
	v_mul_u32_u24_e32 v2, 0x41, v2
	v_lshrrev_b32_e32 v3, 1, v0
	v_lshrrev_b32_e32 v5, 4, v0
	s_movk_i32 s8, 0x3c0
	v_add_lshl_u32 v38, v2, v209, 3
	v_bfe_u32 v2, v25, 4, 6
	v_bitop3_b32 v23, v3, 31, v3 bitop3:0xc
	v_bfe_u32 v3, v0, 4, 1
	v_bfe_u32 v35, v5, 1, 1
	v_and_or_b32 v16, v22, s8, v209
	v_lshlrev_b32_e32 v37, 3, v22
	v_lshlrev_b32_e32 v40, 3, v2
	v_lshlrev_b32_e32 v22, 4, v2
	v_lshrrev_b32_e32 v2, 6, v25
	v_and_b32_e32 v10, 15, v0
	v_lshlrev_b32_e32 v8, 2, v3
	v_mul_u32_u24_e32 v2, 0x41, v2
	v_or_b32_e32 v61, 2, v35
	v_cmp_eq_u32_e64 s[6:7], 0, v3
	v_add_u32_e32 v3, 0, v8
	v_lshlrev_b32_e32 v9, 3, v10
	v_add_lshl_u32 v42, v2, v209, 3
	v_lshlrev_b32_e32 v2, 7, v61
	v_or_b32_e32 v63, 4, v35
	v_add3_u32 v62, v3, v2, v9
	v_lshlrev_b32_e32 v2, 7, v63
	v_or_b32_e32 v65, 6, v35
	v_add3_u32 v64, v3, v2, v9
	v_lshlrev_b32_e32 v2, 7, v65
	v_or_b32_e32 v67, 8, v35
	v_add3_u32 v66, v3, v2, v9
	v_lshlrev_b32_e32 v2, 7, v67
	v_or_b32_e32 v69, 10, v35
	v_add3_u32 v68, v3, v2, v9
	v_lshlrev_b32_e32 v2, 7, v69
	v_or_b32_e32 v71, 12, v35
	v_add3_u32 v70, v3, v2, v9
	v_lshlrev_b32_e32 v2, 7, v71
	v_or_b32_e32 v73, 14, v35
	v_add3_u32 v72, v3, v2, v9
	v_lshlrev_b32_e32 v2, 7, v73
	v_or_b32_e32 v75, 16, v35
	v_add3_u32 v74, v3, v2, v9
	v_lshlrev_b32_e32 v2, 7, v75
	v_or_b32_e32 v77, 18, v35
	v_add3_u32 v76, v3, v2, v9
	v_lshlrev_b32_e32 v2, 7, v77
	v_or_b32_e32 v79, 20, v35
	v_add3_u32 v78, v3, v2, v9
	v_lshlrev_b32_e32 v2, 7, v79
	v_or_b32_e32 v81, 22, v35
	v_add3_u32 v80, v3, v2, v9
	v_lshlrev_b32_e32 v2, 7, v81
	v_or_b32_e32 v83, 24, v35
	v_add3_u32 v82, v3, v2, v9
	v_lshlrev_b32_e32 v2, 7, v83
	v_or_b32_e32 v85, 26, v35
	v_add3_u32 v84, v3, v2, v9
	v_lshlrev_b32_e32 v2, 7, v85
	v_or_b32_e32 v87, 28, v35
	v_add3_u32 v86, v3, v2, v9
	v_lshlrev_b32_e32 v2, 7, v87
	v_or_b32_e32 v89, 30, v35
	v_add3_u32 v88, v3, v2, v9
	v_lshlrev_b32_e32 v2, 7, v89
	v_or_b32_e32 v91, 32, v35
	v_add3_u32 v90, v3, v2, v9
	v_lshlrev_b32_e32 v2, 7, v91
	v_or_b32_e32 v93, 34, v35
	v_add3_u32 v92, v3, v2, v9
	v_lshlrev_b32_e32 v2, 7, v93
	v_or_b32_e32 v95, 36, v35
	v_add3_u32 v94, v3, v2, v9
	v_lshlrev_b32_e32 v2, 7, v95
	v_or_b32_e32 v97, 38, v35
	v_add3_u32 v96, v3, v2, v9
	v_lshlrev_b32_e32 v2, 7, v97
	v_or_b32_e32 v99, 40, v35
	v_add3_u32 v98, v3, v2, v9
	v_lshlrev_b32_e32 v2, 7, v99
	v_or_b32_e32 v101, 42, v35
	v_add3_u32 v100, v3, v2, v9
	v_lshlrev_b32_e32 v2, 7, v101
	v_or_b32_e32 v103, 44, v35
	v_add3_u32 v102, v3, v2, v9
	v_lshlrev_b32_e32 v2, 7, v103
	v_or_b32_e32 v105, 46, v35
	v_add3_u32 v104, v3, v2, v9
	v_lshlrev_b32_e32 v2, 7, v105
	v_or_b32_e32 v107, 48, v35
	v_add3_u32 v106, v3, v2, v9
	v_lshlrev_b32_e32 v2, 7, v107
	v_or_b32_e32 v109, 50, v35
	v_add3_u32 v108, v3, v2, v9
	v_lshlrev_b32_e32 v2, 7, v109
	v_or_b32_e32 v111, 52, v35
	v_add3_u32 v110, v3, v2, v9
	v_lshlrev_b32_e32 v2, 7, v111
	v_or_b32_e32 v113, 54, v35
	v_add3_u32 v112, v3, v2, v9
	v_lshlrev_b32_e32 v2, 7, v113
	v_or_b32_e32 v115, 56, v35
	v_add3_u32 v114, v3, v2, v9
	v_lshlrev_b32_e32 v2, 7, v115
	v_or_b32_e32 v117, 58, v35
	v_add3_u32 v116, v3, v2, v9
	v_lshlrev_b32_e32 v2, 7, v117
	v_or_b32_e32 v119, 60, v35
	v_bfe_u32 v7, v0, 4, 2
	v_add3_u32 v118, v3, v2, v9
	v_lshlrev_b32_e32 v2, 7, v119
	v_or_b32_e32 v121, 62, v35
	v_lshlrev_b32_e32 v24, 2, v7
	v_add3_u32 v120, v3, v2, v9
	v_lshlrev_b32_e32 v2, 7, v121
	v_add3_u32 v122, v3, v2, v9
	v_or_b32_e32 v2, 1, v24
	v_cmp_eq_u32_e64 s[10:11], v2, v10
	v_or_b32_e32 v2, 2, v24
	v_lshlrev_b32_e32 v6, 6, v0
	v_cmp_eq_u32_e64 s[12:13], v2, v10
	v_or_b32_e32 v2, 3, v24
	v_mov_b32_e32 v13, 0
	v_lshlrev_b32_e32 v12, 4, v0
	v_lshlrev_b32_e32 v43, 7, v35
	v_cmp_eq_u32_e64 s[14:15], v2, v10
	v_and_b32_e32 v2, 64, v6
	s_movk_i32 s2, 0x3f0
	v_add3_u32 v60, v3, v43, v9
	v_add_u32_e32 v124, 0, v2
	v_lshl_add_u64 v[2:3], s[56:57], 0, v[12:13]
	s_mov_b64 s[16:17], 0x140000
	v_lshlrev_b32_e32 v12, 11, v10
	v_and_or_b32 v18, v25, s2, v10
	v_and_or_b32 v20, v25, s8, v209
	v_lshlrev_b32_e32 v41, 3, v25
	v_cmp_eq_u32_e64 s[8:9], v24, v10
	v_lshl_add_u64 v[24:25], v[2:3], 0, s[16:17]
	v_lshl_add_u64 v[2:3], s[56:57], 0, v[12:13]
	v_lshlrev_b32_e32 v12, 3, v7
	v_lshl_add_u64 v[2:3], v[2:3], 0, v[12:13]
	s_mov_b64 s[16:17], 0x1a00000
	v_lshl_add_u64 v[26:27], v[2:3], 0, s[16:17]
	v_and_b32_e32 v2, 7, v0
	v_lshlrev_b32_e32 v12, 4, v2
	v_lshl_add_u64 v[2:3], s[56:57], 0, v[12:13]
	s_mov_b64 s[16:17], 0x16300000
	v_lshlrev_b32_e32 v4, 5, v0
	v_lshl_add_u64 v[28:29], v[2:3], 0, s[16:17]
	s_movk_i32 s16, 0x700
	v_and_or_b32 v125, v4, s16, v33
	s_mov_b64 s[16:17], 0x2200000
	s_add_i32 s18, 0, 0x200
	v_lshl_add_u64 v[30:31], v[2:3], 0, s[16:17]
	v_lshrrev_b32_e32 v3, 8, v0
	v_mov_b32_e32 v14, 0x200
	s_add_u32 s54, s56, 0x200000
	v_sub_u32_e32 v126, 32, v3
	v_add_u32_e32 v127, 1, v3
	v_or3_b32 v3, v43, v9, v8
	v_bitop3_b32 v14, v0, s2, v14 bitop3:0xc8
	s_movk_i32 s2, 0x41
	s_addc_u32 s55, s57, 0
	v_add_u32_e32 v3, 0, v3
	s_movk_i32 s3, 0x200
	s_bitcmp1_b32 s92, 0
	v_add_u32_e32 v129, 0x2800, v3
	v_mad_u32_u24 v3, v10, s2, v35
	v_mov_b32_e32 v11, 0x80
	v_lshlrev_b32_e32 v32, 3, v5
	v_add_u32_e32 v39, 0x2080, v58
	s_cselect_b64 s[58:59], -1, 0
	s_bitcmp1_b32 s84, 0
	v_and_or_b32 v2, v6, s3, v5
	v_lshl_add_u32 v3, v3, 3, 0
	v_cmp_lt_u32_e64 s[0:1], v0, v11
	v_cmp_gt_u32_e64 s[4:5], 64, v0
	v_bfe_u32 v21, v0, 1, 5
	v_and_b32_e32 v56, 28, v5
	v_bfe_u32 v57, v0, 4, 4
	v_mul_u32_u24_e32 v59, 0x41, v1
	v_mul_u32_u24_e32 v123, 0x41, v35
	s_cselect_b64 s[60:61], -1, 0
	v_or_b32_e32 v128, 0xffffffe0, v5
	v_add_u32_e32 v130, 0x6880, v3
	s_mov_b32 s3, 0x3fb8aa3b
	s_mov_b32 s24, 0xc2ce8ed0
	s_mov_b32 s25, 0x42b17218
	s_mov_b32 s26, 0x3f22f983
	s_mov_b32 s27, 0xbfc90fda
	v_mov_b32_e32 v131, 0x3c0881c4
	v_mov_b32_e32 v132, 0xbab64f3b
	v_add_u32_e32 v133, 0, v36
	v_add_u32_e32 v134, 0, v37
	v_add_u32_e32 v135, 0, v38
	v_add_u32_e32 v136, 0, v39
	v_add_u32_e32 v137, s18, v40
	v_add_u32_e32 v138, 0, v41
	v_add_u32_e32 v139, 0, v42
	s_mov_b64 s[62:63], 0x400
	s_movk_i32 s33, 0x77
	v_lshlrev_b32_e32 v140, 7, v2
	s_mov_b64 s[68:69], 0x1000
	s_movk_i32 s34, 0x1df
	v_mov_b32_e32 v141, 0x7f800000
	v_not_b32_e32 v142, 63
	v_not_b32_e32 v143, 31
	v_add_u32_e32 v144, 0, v32
	v_add_u32_e32 v145, v19, v34
	s_mov_b32 s35, s92
	v_mov_b32_e32 v146, 0x7fc00000
	v_mov_b32_e32 v147, 0x1f0
	v_or_b32_e32 v32, v14, v10
	v_and_b32_e32 v34, 0x1f0, v0
	v_mov_b32_e32 v36, 1.0
	s_branch .LBB0_42

; __device__ __forceinline__ void prep_ssm(Frame& F) {
;     ...
;     }
;     __syncthreads();
; __device__ __forceinline__ void phase_prep(Frame& F) {
;     ...
;     { prep_tr(F); __syncthreads(); prep_ssm(F); }
.LBB0_71:
	s_waitcnt lgkmcnt(0)
	s_barrier
	s_cmp_lg_u32 s98, 1
	s_cbranch_scc1 .LBB0_72
	s_mov_b32 s98, 2
	v_readlane_b32 s68, v254, 0
	v_readlane_b32 s69, v254, 1
	v_readlane_b32 s72, v254, 2
	v_readlane_b32 s73, v254, 3
	v_lshlrev_b32_e32 v2, 2, v0
	s_nop 3
	s_branch .Lp0_tr

; __global__ void __launch_bounds__(512, 2) mk_fwd(Args args) {
	.amdhsa_kernel _Z6mk_fwd4Args
		.amdhsa_group_segment_fixed_size 0
		.amdhsa_private_segment_fixed_size 0
		.amdhsa_kernarg_size 464
		.amdhsa_user_sgpr_count 2
		.amdhsa_user_sgpr_dispatch_ptr 0
		.amdhsa_user_sgpr_queue_ptr 0
		.amdhsa_user_sgpr_kernarg_segment_ptr 1
		.amdhsa_user_sgpr_dispatch_id 0
		.amdhsa_user_sgpr_kernarg_preload_length 0
		.amdhsa_user_sgpr_kernarg_preload_offset 0
		.amdhsa_user_sgpr_private_segment_size 0
		.amdhsa_uses_dynamic_stack 0
		.amdhsa_enable_private_segment 0
		.amdhsa_system_sgpr_workgroup_id_x 1
		.amdhsa_system_sgpr_workgroup_id_y 0
		.amdhsa_system_sgpr_workgroup_id_z 0
		.amdhsa_system_sgpr_workgroup_info 0
		.amdhsa_system_vgpr_workitem_id 0
		.amdhsa_next_free_vgpr 256
		.amdhsa_next_free_sgpr 102
		.amdhsa_accum_offset 256
		.amdhsa_reserve_vcc 1
		.amdhsa_float_round_mode_32 0
		.amdhsa_float_round_mode_16_64 0
		.amdhsa_float_denorm_mode_32 3
		.amdhsa_float_denorm_mode_16_64 3
		.amdhsa_dx10_clamp 1
		.amdhsa_ieee_mode 1
		.amdhsa_fp16_overflow 0
		.amdhsa_tg_split 0
		.amdhsa_exception_fp_ieee_invalid_op 0
		.amdhsa_exception_fp_denorm_src 0
		.amdhsa_exception_fp_ieee_div_zero 0
		.amdhsa_exception_fp_ieee_overflow 0
		.amdhsa_exception_fp_ieee_underflow 0
		.amdhsa_exception_fp_ieee_inexact 0
		.amdhsa_exception_int_div_zero 0
	.end_amdhsa_kernel

; __global__ void __launch_bounds__(512, 2) mk_fwd(Args args) {
amdhsa.kernels:
  - .agpr_count:     0
    .args:
      - .offset:         0
        .size:           208
        .value_kind:     by_value
      - .offset:         208
        .size:           4
        .value_kind:     hidden_block_count_x
      - .offset:         212
        .size:           4
        .value_kind:     hidden_block_count_y
      - .offset:         216
        .size:           4
        .value_kind:     hidden_block_count_z
      - .offset:         220
        .size:           2
        .value_kind:     hidden_group_size_x
      - .offset:         222
        .size:           2
        .value_kind:     hidden_group_size_y
      - .offset:         224
        .size:           2
        .value_kind:     hidden_group_size_z
      - .offset:         226
        .size:           2
        .value_kind:     hidden_remainder_x
      - .offset:         228
        .size:           2
        .value_kind:     hidden_remainder_y
      - .offset:         230
        .size:           2
        .value_kind:     hidden_remainder_z
      - .offset:         248
        .size:           8
        .value_kind:     hidden_global_offset_x
      - .offset:         256
        .size:           8
        .value_kind:     hidden_global_offset_y
      - .offset:         264
        .size:           8
        .value_kind:     hidden_global_offset_z
      - .offset:         272
        .size:           2
        .value_kind:     hidden_grid_dims
      - .offset:         328
        .size:           4
        .value_kind:     hidden_dynamic_lds_size
    .group_segment_fixed_size: 0
    .kernarg_segment_align: 8
    .kernarg_segment_size: 464
    .language:       OpenCL C
    .language_version:
      - 2
      - 0
    .max_flat_workgroup_size: 512
    .name:           _Z6mk_fwd4Args
    .private_segment_fixed_size: 0
    .sgpr_count:     108
    .sgpr_spill_count: 74
    .symbol:         _Z6mk_fwd4Args.kd
    .uniform_work_group_size: 1
    .uses_dynamic_stack: false
    .vgpr_count:     256
    .vgpr_spill_count: 0
    .wavefront_size: 64
